# M5 + dead DPP-init movs removed in P8 epilogue + P5 attn_norm_row loop software-pipelined (4 rows in flight)
# speedup vs baseline: 1.0104x; 1.0064x over previous
.LBB0_873:
	v_and_b32_e32 v3, 64, v234
	v_add_u32_e32 v3, 64, v3
	v_xor_b32_e32 v4, 1, v234
	s_and_b64 s[6:7], s[6:7], exec
	v_cmp_lt_i32_e32 vcc, v4, v3
	v_xor_b32_e32 v5, 2, v234
	s_cselect_b32 s6, s1, s11
	v_cndmask_b32_e32 v4, v234, v4, vcc
	v_cmp_lt_i32_e32 vcc, v5, v3
	v_xor_b32_e32 v6, 4, v234
	s_ashr_i32 s1, s0, 31
	v_cndmask_b32_e32 v5, v234, v5, vcc
	v_cmp_lt_i32_e32 vcc, v6, v3
	v_xor_b32_e32 v7, 8, v234
	s_lshl_b64 s[0:1], s[0:1], 12
	v_readlane_b32 s7, v254, 47
	v_cndmask_b32_e32 v6, v234, v6, vcc
	v_cmp_lt_i32_e32 vcc, v7, v3
	v_xor_b32_e32 v8, 16, v234
	s_add_u32 s4, s7, s4
	v_readlane_b32 s7, v254, 48
	v_cndmask_b32_e32 v7, v234, v7, vcc
	v_cmp_lt_i32_e32 vcc, v8, v3
	v_xor_b32_e32 v9, 32, v234
	s_addc_u32 s7, s7, 0
	v_cndmask_b32_e32 v8, v234, v8, vcc
	v_cmp_lt_i32_e32 vcc, v9, v3
	v_and_b32_e32 v2, 63, v2
	s_add_u32 s0, s4, s0
	v_cndmask_b32_e32 v3, v234, v9, vcc
	v_lshlrev_b32_e32 v114, 5, v2
	s_addc_u32 s1, s7, s1
	s_ashr_i32 s7, s6, 31
	v_lshlrev_b32_e32 v4, 2, v4
	v_lshlrev_b32_e32 v5, 2, v5
	v_lshlrev_b32_e32 v6, 2, v6
	v_lshlrev_b32_e32 v7, 2, v7
	v_lshlrev_b32_e32 v8, 2, v8
	v_lshlrev_b32_e32 v9, 2, v3
	v_lshl_add_u64 v[2:3], s[0:1], 0, v[114:115]
	s_lshl_b64 s[0:1], s[6:7], 12
	s_cmp_lt_i32 s3, 4
	s_cbranch_scc1 .Lp5_tail
.Lp5_quad:
	v_lshl_add_u64 v[34:35], v[2:3], 0, s[0:1]
	v_lshl_add_u64 v[60:61], v[34:35], 0, s[0:1]
	v_lshl_add_u64 v[62:63], v[60:61], 0, s[0:1]
	global_load_dwordx4 v[10:13], v[2:3], off
	global_load_dwordx4 v[14:17], v[2:3], off offset:16
	global_load_dwordx4 v[36:39], v[34:35], off
	global_load_dwordx4 v[40:43], v[34:35], off offset:16
	global_load_dwordx4 v[44:47], v[60:61], off
	global_load_dwordx4 v[48:51], v[60:61], off offset:16
	global_load_dwordx4 v[52:55], v[62:63], off
	global_load_dwordx4 v[56:59], v[62:63], off offset:16
	s_waitcnt vmcnt(6)
	v_lshlrev_b32_e32 v27, 16, v11
	v_lshlrev_b32_e32 v26, 16, v10
	v_and_b32_e32 v11, 0xffff0000, v11
	v_and_b32_e32 v10, 0xffff0000, v10
	v_pk_mul_f32 v[28:29], v[10:11], v[10:11]
	v_lshlrev_b32_e32 v31, 16, v13
	v_lshlrev_b32_e32 v30, 16, v12
	v_and_b32_e32 v13, 0xffff0000, v13
	v_and_b32_e32 v12, 0xffff0000, v12
	v_pk_fma_f32 v[28:29], v[26:27], v[26:27], v[28:29]
	v_pk_mul_f32 v[32:33], v[12:13], v[12:13]
	v_lshlrev_b32_e32 v19, 16, v15
	v_lshlrev_b32_e32 v18, 16, v14
	v_and_b32_e32 v15, 0xffff0000, v15
	v_and_b32_e32 v14, 0xffff0000, v14
	v_pk_fma_f32 v[32:33], v[30:31], v[30:31], v[32:33]
	v_add_f32_e32 v28, v28, v29
	v_pk_mul_f32 v[20:21], v[14:15], v[14:15]
	v_add_f32_e32 v28, v32, v28
	v_pk_fma_f32 v[20:21], v[18:19], v[18:19], v[20:21]
	v_lshlrev_b32_e32 v23, 16, v17
	v_lshlrev_b32_e32 v22, 16, v16
	v_and_b32_e32 v17, 0xffff0000, v17
	v_and_b32_e32 v16, 0xffff0000, v16
	v_add_f32_e32 v28, v33, v28
	v_pk_mul_f32 v[24:25], v[16:17], v[16:17]
	v_add_f32_e32 v20, v20, v28
	v_pk_fma_f32 v[24:25], v[22:23], v[22:23], v[24:25]
	v_add_f32_e32 v20, v21, v20
	v_add_f32_e32 v20, v24, v20
	v_add_f32_e32 v20, v25, v20
	ds_bpermute_b32 v21, v4, v20
	s_waitcnt lgkmcnt(0)
	v_add_f32_e32 v20, v20, v21
	ds_bpermute_b32 v21, v5, v20
	s_waitcnt lgkmcnt(0)
	v_add_f32_e32 v20, v20, v21
	ds_bpermute_b32 v21, v6, v20
	s_waitcnt lgkmcnt(0)
	v_add_f32_e32 v20, v20, v21
	ds_bpermute_b32 v21, v7, v20
	s_waitcnt lgkmcnt(0)
	v_add_f32_e32 v20, v20, v21
	ds_bpermute_b32 v21, v8, v20
	s_waitcnt lgkmcnt(0)
	v_add_f32_e32 v20, v20, v21
	ds_bpermute_b32 v21, v9, v20
	s_waitcnt lgkmcnt(0)
	v_add_f32_e32 v20, v20, v21
	v_fmamk_f32 v20, v20, 0x3a800000, v1
	v_cmp_gt_f32_e32 vcc, s70, v20
	v_mul_f32_e32 v21, 0x4f800000, v20
	s_nop 0
	v_cndmask_b32_e32 v20, v20, v21, vcc
	v_sqrt_f32_e32 v21, v20
	s_nop 0
	v_add_u32_e32 v24, -1, v21
	v_fma_f32 v25, -v24, v21, v20
	v_cmp_ge_f32_e64 s[36:37], 0, v25
	v_add_u32_e32 v25, 1, v21
	s_nop 0
	v_cndmask_b32_e64 v24, v21, v24, s[36:37]
	v_fma_f32 v21, -v25, v21, v20
	v_cmp_lt_f32_e64 s[36:37], 0, v21
	s_nop 1
	v_cndmask_b32_e64 v21, v24, v25, s[36:37]
	v_mul_f32_e32 v24, 0x37800000, v21
	v_cndmask_b32_e32 v21, v21, v24, vcc
	v_cmp_class_f32_e32 vcc, v20, v226
	s_nop 1
	v_cndmask_b32_e32 v20, v21, v20, vcc
	v_div_scale_f32 v21, s[6:7], v20, v20, 1.0
	v_rcp_f32_e32 v24, v21
	s_nop 0
	v_fma_f32 v25, -v21, v24, 1.0
	v_fmac_f32_e32 v24, v25, v24
	v_div_scale_f32 v25, vcc, 1.0, v20, 1.0
	v_mul_f32_e32 v28, v25, v24
	v_fma_f32 v29, -v21, v28, v25
	v_fmac_f32_e32 v28, v29, v24
	v_fma_f32 v21, -v21, v28, v25
	v_div_fmas_f32 v21, v21, v24, v28
	v_div_fixup_f32 v20, v21, v20, 1.0
	v_pk_mul_f32 v[12:13], v[20:21], v[12:13] op_sel_hi:[0,1]
	v_pk_mul_f32 v[24:25], v[20:21], v[26:27] op_sel_hi:[0,1]
	v_pk_mul_f32 v[10:11], v[20:21], v[10:11] op_sel_hi:[0,1]
	v_pk_mul_f32 v[26:27], v[20:21], v[30:31] op_sel_hi:[0,1]
	v_bfe_u32 v21, v13, 16, 1
	v_bfe_u32 v28, v12, 16, 1
	v_bfe_u32 v29, v11, 16, 1
	v_add3_u32 v13, v13, v21, s67
	v_bfe_u32 v21, v24, 16, 1
	v_add3_u32 v11, v11, v29, s67
	v_add3_u32 v12, v12, v28, s67
	v_bfe_u32 v28, v25, 16, 1
	v_bfe_u32 v29, v26, 16, 1
	v_add3_u32 v21, v24, v21, s67
	v_bfe_u32 v30, v10, 16, 1
	v_add3_u32 v26, v26, v29, s67
	v_add3_u32 v25, v25, v28, s67
	v_lshrrev_b32_e32 v21, 16, v21
	v_add3_u32 v10, v10, v30, s67
	v_lshrrev_b32_e32 v24, 16, v25
	v_lshrrev_b32_e32 v25, 16, v26
	v_pk_mul_f32 v[14:15], v[20:21], v[14:15] op_sel_hi:[0,1]
	v_pk_mul_f32 v[16:17], v[20:21], v[16:17] op_sel_hi:[0,1]
	v_bfe_u32 v30, v27, 16, 1
	v_and_or_b32 v12, v12, s8, v25
	v_and_or_b32 v11, v11, s8, v24
	v_and_or_b32 v10, v10, s8, v21
	v_pk_mul_f32 v[18:19], v[20:21], v[18:19] op_sel_hi:[0,1]
	v_pk_mul_f32 v[22:23], v[20:21], v[22:23] op_sel_hi:[0,1]
	v_bfe_u32 v20, v17, 16, 1
	v_bfe_u32 v21, v16, 16, 1
	v_bfe_u32 v24, v15, 16, 1
	v_bfe_u32 v25, v14, 16, 1
	v_add3_u32 v27, v27, v30, s67
	v_add3_u32 v14, v14, v25, s67
	v_add3_u32 v15, v15, v24, s67
	v_add3_u32 v16, v16, v21, s67
	v_add3_u32 v17, v17, v20, s67
	v_bfe_u32 v20, v18, 16, 1
	v_bfe_u32 v21, v19, 16, 1
	v_bfe_u32 v24, v22, 16, 1
	v_bfe_u32 v25, v23, 16, 1
	v_lshrrev_b32_e32 v26, 16, v27
	v_add3_u32 v23, v23, v25, s67
	v_add3_u32 v22, v22, v24, s67
	v_add3_u32 v19, v19, v21, s67
	v_add3_u32 v18, v18, v20, s67
	v_and_or_b32 v13, v13, s8, v26
	v_lshrrev_b32_e32 v18, 16, v18
	v_lshrrev_b32_e32 v19, 16, v19
	v_lshrrev_b32_e32 v20, 16, v22
	v_lshrrev_b32_e32 v21, 16, v23
	v_and_or_b32 v17, v17, s8, v21
	v_and_or_b32 v16, v16, s8, v20
	v_and_or_b32 v15, v15, s8, v19
	v_and_or_b32 v14, v14, s8, v18
	global_store_dwordx4 v[2:3], v[10:13], off
	global_store_dwordx4 v[2:3], v[14:17], off offset:16
	s_waitcnt vmcnt(6)
	v_lshlrev_b32_e32 v27, 16, v37
	v_lshlrev_b32_e32 v26, 16, v36
	v_and_b32_e32 v37, 0xffff0000, v37
	v_and_b32_e32 v36, 0xffff0000, v36
	v_pk_mul_f32 v[28:29], v[36:37], v[36:37]
	v_lshlrev_b32_e32 v31, 16, v39
	v_lshlrev_b32_e32 v30, 16, v38
	v_and_b32_e32 v39, 0xffff0000, v39
	v_and_b32_e32 v38, 0xffff0000, v38
	v_pk_fma_f32 v[28:29], v[26:27], v[26:27], v[28:29]
	v_pk_mul_f32 v[32:33], v[38:39], v[38:39]
	v_lshlrev_b32_e32 v19, 16, v41
	v_lshlrev_b32_e32 v18, 16, v40
	v_and_b32_e32 v41, 0xffff0000, v41
	v_and_b32_e32 v40, 0xffff0000, v40
	v_pk_fma_f32 v[32:33], v[30:31], v[30:31], v[32:33]
	v_add_f32_e32 v28, v28, v29
	v_pk_mul_f32 v[20:21], v[40:41], v[40:41]
	v_add_f32_e32 v28, v32, v28
	v_pk_fma_f32 v[20:21], v[18:19], v[18:19], v[20:21]
	v_lshlrev_b32_e32 v23, 16, v43
	v_lshlrev_b32_e32 v22, 16, v42
	v_and_b32_e32 v43, 0xffff0000, v43
	v_and_b32_e32 v42, 0xffff0000, v42
	v_add_f32_e32 v28, v33, v28
	v_pk_mul_f32 v[24:25], v[42:43], v[42:43]
	v_add_f32_e32 v20, v20, v28
	v_pk_fma_f32 v[24:25], v[22:23], v[22:23], v[24:25]
	v_add_f32_e32 v20, v21, v20
	v_add_f32_e32 v20, v24, v20
	v_add_f32_e32 v20, v25, v20
	ds_bpermute_b32 v21, v4, v20
	s_waitcnt lgkmcnt(0)
	v_add_f32_e32 v20, v20, v21
	ds_bpermute_b32 v21, v5, v20
	s_waitcnt lgkmcnt(0)
	v_add_f32_e32 v20, v20, v21
	ds_bpermute_b32 v21, v6, v20
	s_waitcnt lgkmcnt(0)
	v_add_f32_e32 v20, v20, v21
	ds_bpermute_b32 v21, v7, v20
	s_waitcnt lgkmcnt(0)
	v_add_f32_e32 v20, v20, v21
	ds_bpermute_b32 v21, v8, v20
	s_waitcnt lgkmcnt(0)
	v_add_f32_e32 v20, v20, v21
	ds_bpermute_b32 v21, v9, v20
	s_waitcnt lgkmcnt(0)
	v_add_f32_e32 v20, v20, v21
	v_fmamk_f32 v20, v20, 0x3a800000, v1
	v_cmp_gt_f32_e32 vcc, s70, v20
	v_mul_f32_e32 v21, 0x4f800000, v20
	s_nop 0
	v_cndmask_b32_e32 v20, v20, v21, vcc
	v_sqrt_f32_e32 v21, v20
	s_nop 0
	v_add_u32_e32 v24, -1, v21
	v_fma_f32 v25, -v24, v21, v20
	v_cmp_ge_f32_e64 s[36:37], 0, v25
	v_add_u32_e32 v25, 1, v21
	s_nop 0
	v_cndmask_b32_e64 v24, v21, v24, s[36:37]
	v_fma_f32 v21, -v25, v21, v20
	v_cmp_lt_f32_e64 s[36:37], 0, v21
	s_nop 1
	v_cndmask_b32_e64 v21, v24, v25, s[36:37]
	v_mul_f32_e32 v24, 0x37800000, v21
	v_cndmask_b32_e32 v21, v21, v24, vcc
	v_cmp_class_f32_e32 vcc, v20, v226
	s_nop 1
	v_cndmask_b32_e32 v20, v21, v20, vcc
	v_div_scale_f32 v21, s[6:7], v20, v20, 1.0
	v_rcp_f32_e32 v24, v21
	s_nop 0
	v_fma_f32 v25, -v21, v24, 1.0
	v_fmac_f32_e32 v24, v25, v24
	v_div_scale_f32 v25, vcc, 1.0, v20, 1.0
	v_mul_f32_e32 v28, v25, v24
	v_fma_f32 v29, -v21, v28, v25
	v_fmac_f32_e32 v28, v29, v24
	v_fma_f32 v21, -v21, v28, v25
	v_div_fmas_f32 v21, v21, v24, v28
	v_div_fixup_f32 v20, v21, v20, 1.0
	v_pk_mul_f32 v[38:39], v[20:21], v[38:39] op_sel_hi:[0,1]
	v_pk_mul_f32 v[24:25], v[20:21], v[26:27] op_sel_hi:[0,1]
	v_pk_mul_f32 v[36:37], v[20:21], v[36:37] op_sel_hi:[0,1]
	v_pk_mul_f32 v[26:27], v[20:21], v[30:31] op_sel_hi:[0,1]
	v_bfe_u32 v21, v39, 16, 1
	v_bfe_u32 v28, v38, 16, 1
	v_bfe_u32 v29, v37, 16, 1
	v_add3_u32 v39, v39, v21, s67
	v_bfe_u32 v21, v24, 16, 1
	v_add3_u32 v37, v37, v29, s67
	v_add3_u32 v38, v38, v28, s67
	v_bfe_u32 v28, v25, 16, 1
	v_bfe_u32 v29, v26, 16, 1
	v_add3_u32 v21, v24, v21, s67
	v_bfe_u32 v30, v36, 16, 1
	v_add3_u32 v26, v26, v29, s67
	v_add3_u32 v25, v25, v28, s67
	v_lshrrev_b32_e32 v21, 16, v21
	v_add3_u32 v36, v36, v30, s67
	v_lshrrev_b32_e32 v24, 16, v25
	v_lshrrev_b32_e32 v25, 16, v26
	v_pk_mul_f32 v[40:41], v[20:21], v[40:41] op_sel_hi:[0,1]
	v_pk_mul_f32 v[42:43], v[20:21], v[42:43] op_sel_hi:[0,1]
	v_bfe_u32 v30, v27, 16, 1
	v_and_or_b32 v38, v38, s8, v25
	v_and_or_b32 v37, v37, s8, v24
	v_and_or_b32 v36, v36, s8, v21
	v_pk_mul_f32 v[18:19], v[20:21], v[18:19] op_sel_hi:[0,1]
	v_pk_mul_f32 v[22:23], v[20:21], v[22:23] op_sel_hi:[0,1]
	v_bfe_u32 v20, v43, 16, 1
	v_bfe_u32 v21, v42, 16, 1
	v_bfe_u32 v24, v41, 16, 1
	v_bfe_u32 v25, v40, 16, 1
	v_add3_u32 v27, v27, v30, s67
	v_add3_u32 v40, v40, v25, s67
	v_add3_u32 v41, v41, v24, s67
	v_add3_u32 v42, v42, v21, s67
	v_add3_u32 v43, v43, v20, s67
	v_bfe_u32 v20, v18, 16, 1
	v_bfe_u32 v21, v19, 16, 1
	v_bfe_u32 v24, v22, 16, 1
	v_bfe_u32 v25, v23, 16, 1
	v_lshrrev_b32_e32 v26, 16, v27
	v_add3_u32 v23, v23, v25, s67
	v_add3_u32 v22, v22, v24, s67
	v_add3_u32 v19, v19, v21, s67
	v_add3_u32 v18, v18, v20, s67
	v_and_or_b32 v39, v39, s8, v26
	v_lshrrev_b32_e32 v18, 16, v18
	v_lshrrev_b32_e32 v19, 16, v19
	v_lshrrev_b32_e32 v20, 16, v22
	v_lshrrev_b32_e32 v21, 16, v23
	v_and_or_b32 v43, v43, s8, v21
	v_and_or_b32 v42, v42, s8, v20
	v_and_or_b32 v41, v41, s8, v19
	v_and_or_b32 v40, v40, s8, v18
	global_store_dwordx4 v[34:35], v[36:39], off
	global_store_dwordx4 v[34:35], v[40:43], off offset:16
	s_waitcnt vmcnt(6)
	v_lshlrev_b32_e32 v27, 16, v45
	v_lshlrev_b32_e32 v26, 16, v44
	v_and_b32_e32 v45, 0xffff0000, v45
	v_and_b32_e32 v44, 0xffff0000, v44
	v_pk_mul_f32 v[28:29], v[44:45], v[44:45]
	v_lshlrev_b32_e32 v31, 16, v47
	v_lshlrev_b32_e32 v30, 16, v46
	v_and_b32_e32 v47, 0xffff0000, v47
	v_and_b32_e32 v46, 0xffff0000, v46
	v_pk_fma_f32 v[28:29], v[26:27], v[26:27], v[28:29]
	v_pk_mul_f32 v[32:33], v[46:47], v[46:47]
	v_lshlrev_b32_e32 v19, 16, v49
	v_lshlrev_b32_e32 v18, 16, v48
	v_and_b32_e32 v49, 0xffff0000, v49
	v_and_b32_e32 v48, 0xffff0000, v48
	v_pk_fma_f32 v[32:33], v[30:31], v[30:31], v[32:33]
	v_add_f32_e32 v28, v28, v29
	v_pk_mul_f32 v[20:21], v[48:49], v[48:49]
	v_add_f32_e32 v28, v32, v28
	v_pk_fma_f32 v[20:21], v[18:19], v[18:19], v[20:21]
	v_lshlrev_b32_e32 v23, 16, v51
	v_lshlrev_b32_e32 v22, 16, v50
	v_and_b32_e32 v51, 0xffff0000, v51
	v_and_b32_e32 v50, 0xffff0000, v50
	v_add_f32_e32 v28, v33, v28
	v_pk_mul_f32 v[24:25], v[50:51], v[50:51]
	v_add_f32_e32 v20, v20, v28
	v_pk_fma_f32 v[24:25], v[22:23], v[22:23], v[24:25]
	v_add_f32_e32 v20, v21, v20
	v_add_f32_e32 v20, v24, v20
	v_add_f32_e32 v20, v25, v20
	ds_bpermute_b32 v21, v4, v20
	s_waitcnt lgkmcnt(0)
	v_add_f32_e32 v20, v20, v21
	ds_bpermute_b32 v21, v5, v20
	s_waitcnt lgkmcnt(0)
	v_add_f32_e32 v20, v20, v21
	ds_bpermute_b32 v21, v6, v20
	s_waitcnt lgkmcnt(0)
	v_add_f32_e32 v20, v20, v21
	ds_bpermute_b32 v21, v7, v20
	s_waitcnt lgkmcnt(0)
	v_add_f32_e32 v20, v20, v21
	ds_bpermute_b32 v21, v8, v20
	s_waitcnt lgkmcnt(0)
	v_add_f32_e32 v20, v20, v21
	ds_bpermute_b32 v21, v9, v20
	s_waitcnt lgkmcnt(0)
	v_add_f32_e32 v20, v20, v21
	v_fmamk_f32 v20, v20, 0x3a800000, v1
	v_cmp_gt_f32_e32 vcc, s70, v20
	v_mul_f32_e32 v21, 0x4f800000, v20
	s_nop 0
	v_cndmask_b32_e32 v20, v20, v21, vcc
	v_sqrt_f32_e32 v21, v20
	s_nop 0
	v_add_u32_e32 v24, -1, v21
	v_fma_f32 v25, -v24, v21, v20
	v_cmp_ge_f32_e64 s[36:37], 0, v25
	v_add_u32_e32 v25, 1, v21
	s_nop 0
	v_cndmask_b32_e64 v24, v21, v24, s[36:37]
	v_fma_f32 v21, -v25, v21, v20
	v_cmp_lt_f32_e64 s[36:37], 0, v21
	s_nop 1
	v_cndmask_b32_e64 v21, v24, v25, s[36:37]
	v_mul_f32_e32 v24, 0x37800000, v21
	v_cndmask_b32_e32 v21, v21, v24, vcc
	v_cmp_class_f32_e32 vcc, v20, v226
	s_nop 1
	v_cndmask_b32_e32 v20, v21, v20, vcc
	v_div_scale_f32 v21, s[6:7], v20, v20, 1.0
	v_rcp_f32_e32 v24, v21
	s_nop 0
	v_fma_f32 v25, -v21, v24, 1.0
	v_fmac_f32_e32 v24, v25, v24
	v_div_scale_f32 v25, vcc, 1.0, v20, 1.0
	v_mul_f32_e32 v28, v25, v24
	v_fma_f32 v29, -v21, v28, v25
	v_fmac_f32_e32 v28, v29, v24
	v_fma_f32 v21, -v21, v28, v25
	v_div_fmas_f32 v21, v21, v24, v28
	v_div_fixup_f32 v20, v21, v20, 1.0
	v_pk_mul_f32 v[46:47], v[20:21], v[46:47] op_sel_hi:[0,1]
	v_pk_mul_f32 v[24:25], v[20:21], v[26:27] op_sel_hi:[0,1]
	v_pk_mul_f32 v[44:45], v[20:21], v[44:45] op_sel_hi:[0,1]
	v_pk_mul_f32 v[26:27], v[20:21], v[30:31] op_sel_hi:[0,1]
	v_bfe_u32 v21, v47, 16, 1
	v_bfe_u32 v28, v46, 16, 1
	v_bfe_u32 v29, v45, 16, 1
	v_add3_u32 v47, v47, v21, s67
	v_bfe_u32 v21, v24, 16, 1
	v_add3_u32 v45, v45, v29, s67
	v_add3_u32 v46, v46, v28, s67
	v_bfe_u32 v28, v25, 16, 1
	v_bfe_u32 v29, v26, 16, 1
	v_add3_u32 v21, v24, v21, s67
	v_bfe_u32 v30, v44, 16, 1
	v_add3_u32 v26, v26, v29, s67
	v_add3_u32 v25, v25, v28, s67
	v_lshrrev_b32_e32 v21, 16, v21
	v_add3_u32 v44, v44, v30, s67
	v_lshrrev_b32_e32 v24, 16, v25
	v_lshrrev_b32_e32 v25, 16, v26
	v_pk_mul_f32 v[48:49], v[20:21], v[48:49] op_sel_hi:[0,1]
	v_pk_mul_f32 v[50:51], v[20:21], v[50:51] op_sel_hi:[0,1]
	v_bfe_u32 v30, v27, 16, 1
	v_and_or_b32 v46, v46, s8, v25
	v_and_or_b32 v45, v45, s8, v24
	v_and_or_b32 v44, v44, s8, v21
	v_pk_mul_f32 v[18:19], v[20:21], v[18:19] op_sel_hi:[0,1]
	v_pk_mul_f32 v[22:23], v[20:21], v[22:23] op_sel_hi:[0,1]
	v_bfe_u32 v20, v51, 16, 1
	v_bfe_u32 v21, v50, 16, 1
	v_bfe_u32 v24, v49, 16, 1
	v_bfe_u32 v25, v48, 16, 1
	v_add3_u32 v27, v27, v30, s67
	v_add3_u32 v48, v48, v25, s67
	v_add3_u32 v49, v49, v24, s67
	v_add3_u32 v50, v50, v21, s67
	v_add3_u32 v51, v51, v20, s67
	v_bfe_u32 v20, v18, 16, 1
	v_bfe_u32 v21, v19, 16, 1
	v_bfe_u32 v24, v22, 16, 1
	v_bfe_u32 v25, v23, 16, 1
	v_lshrrev_b32_e32 v26, 16, v27
	v_add3_u32 v23, v23, v25, s67
	v_add3_u32 v22, v22, v24, s67
	v_add3_u32 v19, v19, v21, s67
	v_add3_u32 v18, v18, v20, s67
	v_and_or_b32 v47, v47, s8, v26
	v_lshrrev_b32_e32 v18, 16, v18
	v_lshrrev_b32_e32 v19, 16, v19
	v_lshrrev_b32_e32 v20, 16, v22
	v_lshrrev_b32_e32 v21, 16, v23
	v_and_or_b32 v51, v51, s8, v21
	v_and_or_b32 v50, v50, s8, v20
	v_and_or_b32 v49, v49, s8, v19
	v_and_or_b32 v48, v48, s8, v18
	global_store_dwordx4 v[60:61], v[44:47], off
	global_store_dwordx4 v[60:61], v[48:51], off offset:16
	s_waitcnt vmcnt(6)
	v_lshlrev_b32_e32 v27, 16, v53
	v_lshlrev_b32_e32 v26, 16, v52
	v_and_b32_e32 v53, 0xffff0000, v53
	v_and_b32_e32 v52, 0xffff0000, v52
	v_pk_mul_f32 v[28:29], v[52:53], v[52:53]
	v_lshlrev_b32_e32 v31, 16, v55
	v_lshlrev_b32_e32 v30, 16, v54
	v_and_b32_e32 v55, 0xffff0000, v55
	v_and_b32_e32 v54, 0xffff0000, v54
	v_pk_fma_f32 v[28:29], v[26:27], v[26:27], v[28:29]
	v_pk_mul_f32 v[32:33], v[54:55], v[54:55]
	v_lshlrev_b32_e32 v19, 16, v57
	v_lshlrev_b32_e32 v18, 16, v56
	v_and_b32_e32 v57, 0xffff0000, v57
	v_and_b32_e32 v56, 0xffff0000, v56
	v_pk_fma_f32 v[32:33], v[30:31], v[30:31], v[32:33]
	v_add_f32_e32 v28, v28, v29
	v_pk_mul_f32 v[20:21], v[56:57], v[56:57]
	v_add_f32_e32 v28, v32, v28
	v_pk_fma_f32 v[20:21], v[18:19], v[18:19], v[20:21]
	v_lshlrev_b32_e32 v23, 16, v59
	v_lshlrev_b32_e32 v22, 16, v58
	v_and_b32_e32 v59, 0xffff0000, v59
	v_and_b32_e32 v58, 0xffff0000, v58
	v_add_f32_e32 v28, v33, v28
	v_pk_mul_f32 v[24:25], v[58:59], v[58:59]
	v_add_f32_e32 v20, v20, v28
	v_pk_fma_f32 v[24:25], v[22:23], v[22:23], v[24:25]
	v_add_f32_e32 v20, v21, v20
	v_add_f32_e32 v20, v24, v20
	v_add_f32_e32 v20, v25, v20
	ds_bpermute_b32 v21, v4, v20
	s_waitcnt lgkmcnt(0)
	v_add_f32_e32 v20, v20, v21
	ds_bpermute_b32 v21, v5, v20
	s_waitcnt lgkmcnt(0)
	v_add_f32_e32 v20, v20, v21
	ds_bpermute_b32 v21, v6, v20
	s_waitcnt lgkmcnt(0)
	v_add_f32_e32 v20, v20, v21
	ds_bpermute_b32 v21, v7, v20
	s_waitcnt lgkmcnt(0)
	v_add_f32_e32 v20, v20, v21
	ds_bpermute_b32 v21, v8, v20
	s_waitcnt lgkmcnt(0)
	v_add_f32_e32 v20, v20, v21
	ds_bpermute_b32 v21, v9, v20
	s_waitcnt lgkmcnt(0)
	v_add_f32_e32 v20, v20, v21
	v_fmamk_f32 v20, v20, 0x3a800000, v1
	v_cmp_gt_f32_e32 vcc, s70, v20
	v_mul_f32_e32 v21, 0x4f800000, v20
	s_nop 0
	v_cndmask_b32_e32 v20, v20, v21, vcc
	v_sqrt_f32_e32 v21, v20
	s_nop 0
	v_add_u32_e32 v24, -1, v21
	v_fma_f32 v25, -v24, v21, v20
	v_cmp_ge_f32_e64 s[36:37], 0, v25
	v_add_u32_e32 v25, 1, v21
	s_nop 0
	v_cndmask_b32_e64 v24, v21, v24, s[36:37]
	v_fma_f32 v21, -v25, v21, v20
	v_cmp_lt_f32_e64 s[36:37], 0, v21
	s_nop 1
	v_cndmask_b32_e64 v21, v24, v25, s[36:37]
	v_mul_f32_e32 v24, 0x37800000, v21
	v_cndmask_b32_e32 v21, v21, v24, vcc
	v_cmp_class_f32_e32 vcc, v20, v226
	s_nop 1
	v_cndmask_b32_e32 v20, v21, v20, vcc
	v_div_scale_f32 v21, s[6:7], v20, v20, 1.0
	v_rcp_f32_e32 v24, v21
	s_nop 0
	v_fma_f32 v25, -v21, v24, 1.0
	v_fmac_f32_e32 v24, v25, v24
	v_div_scale_f32 v25, vcc, 1.0, v20, 1.0
	v_mul_f32_e32 v28, v25, v24
	v_fma_f32 v29, -v21, v28, v25
	v_fmac_f32_e32 v28, v29, v24
	v_fma_f32 v21, -v21, v28, v25
	v_div_fmas_f32 v21, v21, v24, v28
	v_div_fixup_f32 v20, v21, v20, 1.0
	v_pk_mul_f32 v[54:55], v[20:21], v[54:55] op_sel_hi:[0,1]
	v_pk_mul_f32 v[24:25], v[20:21], v[26:27] op_sel_hi:[0,1]
	v_pk_mul_f32 v[52:53], v[20:21], v[52:53] op_sel_hi:[0,1]
	v_pk_mul_f32 v[26:27], v[20:21], v[30:31] op_sel_hi:[0,1]
	v_bfe_u32 v21, v55, 16, 1
	v_bfe_u32 v28, v54, 16, 1
	v_bfe_u32 v29, v53, 16, 1
	v_add3_u32 v55, v55, v21, s67
	v_bfe_u32 v21, v24, 16, 1
	v_add3_u32 v53, v53, v29, s67
	v_add3_u32 v54, v54, v28, s67
	v_bfe_u32 v28, v25, 16, 1
	v_bfe_u32 v29, v26, 16, 1
	v_add3_u32 v21, v24, v21, s67
	v_bfe_u32 v30, v52, 16, 1
	v_add3_u32 v26, v26, v29, s67
	v_add3_u32 v25, v25, v28, s67
	v_lshrrev_b32_e32 v21, 16, v21
	v_add3_u32 v52, v52, v30, s67
	v_lshrrev_b32_e32 v24, 16, v25
	v_lshrrev_b32_e32 v25, 16, v26
	v_pk_mul_f32 v[56:57], v[20:21], v[56:57] op_sel_hi:[0,1]
	v_pk_mul_f32 v[58:59], v[20:21], v[58:59] op_sel_hi:[0,1]
	v_bfe_u32 v30, v27, 16, 1
	v_and_or_b32 v54, v54, s8, v25
	v_and_or_b32 v53, v53, s8, v24
	v_and_or_b32 v52, v52, s8, v21
	v_pk_mul_f32 v[18:19], v[20:21], v[18:19] op_sel_hi:[0,1]
	v_pk_mul_f32 v[22:23], v[20:21], v[22:23] op_sel_hi:[0,1]
	v_bfe_u32 v20, v59, 16, 1
	v_bfe_u32 v21, v58, 16, 1
	v_bfe_u32 v24, v57, 16, 1
	v_bfe_u32 v25, v56, 16, 1
	v_add3_u32 v27, v27, v30, s67
	v_add3_u32 v56, v56, v25, s67
	v_add3_u32 v57, v57, v24, s67
	v_add3_u32 v58, v58, v21, s67
	v_add3_u32 v59, v59, v20, s67
	v_bfe_u32 v20, v18, 16, 1
	v_bfe_u32 v21, v19, 16, 1
	v_bfe_u32 v24, v22, 16, 1
	v_bfe_u32 v25, v23, 16, 1
	v_lshrrev_b32_e32 v26, 16, v27
	v_add3_u32 v23, v23, v25, s67
	v_add3_u32 v22, v22, v24, s67
	v_add3_u32 v19, v19, v21, s67
	v_add3_u32 v18, v18, v20, s67
	v_and_or_b32 v55, v55, s8, v26
	v_lshrrev_b32_e32 v18, 16, v18
	v_lshrrev_b32_e32 v19, 16, v19
	v_lshrrev_b32_e32 v20, 16, v22
	v_lshrrev_b32_e32 v21, 16, v23
	v_and_or_b32 v59, v59, s8, v21
	v_and_or_b32 v58, v58, s8, v20
	v_and_or_b32 v57, v57, s8, v19
	v_and_or_b32 v56, v56, s8, v18
	global_store_dwordx4 v[62:63], v[52:55], off
	global_store_dwordx4 v[62:63], v[56:59], off offset:16
	v_lshl_add_u64 v[2:3], v[62:63], 0, s[0:1]
	s_add_i32 s3, s3, -4
	s_cmp_lt_i32 s3, 4
	s_cbranch_scc0 .Lp5_quad
.Lp5_tail:
	s_cmp_lt_i32 s3, 1
	s_cbranch_scc1 .LBB0_875

.LBB0_1120:
	s_or_b64 exec, exec, s[78:79]
	v_lshlrev_b64 v[108:109], 2, v[170:171]
	s_waitcnt lgkmcnt(0)
	s_barrier
	v_lshl_add_u64 v[182:183], s[8:9], 0, v[108:109]
	v_lshl_add_u64 v[184:185], s[18:19], 0, v[108:109]
	global_load_dwordx4 v[146:149], v[182:183], off
	global_load_dwordx4 v[138:141], v[184:185], off
	v_lshl_add_u64 v[186:187], s[20:21], 0, v[108:109]
	global_load_dwordx4 v[142:145], v[186:187], off
	v_lshl_add_u64 v[188:189], s[10:11], 0, v[108:109]
	global_load_dwordx4 v[150:153], v[188:189], off
	v_cvt_f32_i32_e32 v119, v119
	v_cvt_f32_i32_e32 v118, v118
	v_cvt_f32_i32_e32 v117, v117
	v_cvt_f32_i32_e32 v116, v116
	v_cvt_f32_i32_e32 v109, v125
	v_cvt_f32_i32_e32 v108, v124
	v_cvt_f32_i32_e32 v125, v127
	v_cvt_f32_i32_e32 v124, v126
	v_cvt_f32_i32_e32 v127, v121
	v_cvt_f32_i32_e32 v126, v120
	v_mul_f32_e32 v136, 0x3c010204, v136
	v_mov_b32_e32 v120, v198
	v_mov_b32_e32 v121, v198
	v_mov_b32_e32 v199, v198
	v_pk_mul_f32 v[120:121], v[136:137], v[120:121] op_sel_hi:[0,1]
	v_mov_b32_e32 v191, v190
	v_cvt_f32_i32_e32 v203, v123
	v_cvt_f32_i32_e32 v202, v122
	v_pk_mul_f32 v[122:123], v[136:137], v[198:199] op_sel_hi:[0,1]
	v_pk_mul_f32 v[118:119], v[120:121], v[118:119]
	v_mov_b32_e32 v120, v190
	v_mov_b32_e32 v121, v190
	v_pk_mul_f32 v[116:117], v[122:123], v[116:117]
	v_pk_mul_f32 v[122:123], v[120:121], v[194:195] op_sel_hi:[1,0]
	v_pk_mul_f32 v[204:205], v[190:191], v[194:195] op_sel_hi:[1,0]
	v_pk_mul_f32 v[200:201], v[122:123], v[124:125]
	v_pk_mul_f32 v[204:205], v[204:205], v[108:109]
	v_pk_mul_f32 v[108:109], v[120:121], v[192:193] op_sel_hi:[1,0]
	ds_read_b128 v[120:123], v211
	v_pk_mul_f32 v[124:125], v[190:191], v[192:193] op_sel_hi:[1,0]
	v_pk_mul_f32 v[108:109], v[108:109], v[202:203]
	v_pk_mul_f32 v[202:203], v[124:125], v[126:127]
	ds_read_b128 v[124:127], v212 offset:1024
	s_waitcnt lgkmcnt(1)
	v_pk_mul_f32 v[220:221], v[122:123], 0 op_sel_hi:[1,0]
	v_pk_mul_f32 v[222:223], v[120:121], 0 op_sel_hi:[1,0]
	v_cndmask_b32_e64 v160, v123, v221, s[36:37]
	v_cndmask_b32_e64 v120, v120, v222, s[36:37]
	v_cndmask_b32_e64 v121, v121, v223, s[36:37]
	v_cndmask_b32_e64 v137, v122, v220, s[36:37]
	v_mov_b32_dpp v221, v132 row_ror:1 row_mask:0xf bank_mask:0xf
	v_mov_b32_dpp v240, v133 row_ror:1 row_mask:0xf bank_mask:0xf
	v_mov_b32_dpp v122, v132 row_ror:15 row_mask:0xf bank_mask:0xf
	v_mov_b32_dpp v224, v204 row_ror:15 row_mask:0xf bank_mask:0xf
	v_mov_b32_dpp v123, v133 row_ror:15 row_mask:0xf bank_mask:0xf
	v_mov_b32_dpp v243, v205 row_ror:15 row_mask:0xf bank_mask:0xf
	v_cndmask_b32_e64 v121, v240, v121, s[38:39]
	v_cndmask_b32_e64 v120, v221, v120, s[38:39]
	v_cndmask_b32_e64 v123, v123, v243, s[40:41]
	v_cndmask_b32_e64 v122, v122, v224, s[40:41]
	v_mov_b32_dpp v246, v134 row_ror:1 row_mask:0xf bank_mask:0xf
	v_mov_b32_dpp v251, v135 row_ror:1 row_mask:0xf bank_mask:0xf
	v_mov_b32_dpp v249, v200 row_ror:15 row_mask:0xf bank_mask:0xf
	v_mov_b32_dpp v161, v135 row_ror:15 row_mask:0xf bank_mask:0xf
	v_mov_b32_dpp v252, v201 row_ror:15 row_mask:0xf bank_mask:0xf
	v_cndmask_b32_e64 v161, v161, v252, s[40:41]
	s_mul_i32 s78, s76, 6
	s_waitcnt vmcnt(2)
	v_pk_mul_f32 v[230:231], v[132:133], v[138:139]
	v_pk_mul_f32 v[232:233], v[134:135], v[140:141]
	v_pk_fma_f32 v[120:121], v[146:147], v[120:121], v[230:231]
	s_waitcnt vmcnt(1)
	v_pk_fma_f32 v[120:121], v[142:143], v[122:123], v[120:121]
	v_cndmask_b32_e64 v123, v251, v160, s[38:39]
	v_mov_b32_dpp v231, v134 row_ror:15 row_mask:0xf bank_mask:0xf
	v_cndmask_b32_e64 v122, v246, v137, s[38:39]
	v_cndmask_b32_e64 v160, v231, v249, s[40:41]
	v_pk_fma_f32 v[122:123], v[148:149], v[122:123], v[232:233]
	v_pk_fma_f32 v[122:123], v[144:145], v[160:161], v[122:123]
	v_mov_b32_e32 v181, v180
	v_mov_b32_e32 v197, v196
	v_mov_b32_e32 v179, v178
	v_mov_b32_e32 v177, v176
	v_mov_b32_dpp v107, v204 row_ror:1 row_mask:0xf bank_mask:0xf
	v_mov_b32_dpp v114, v202 row_ror:1 row_mask:0xf bank_mask:0xf
	v_mov_b32_dpp v173, v202 row_ror:15 row_mask:0xf bank_mask:0xf
	v_mov_b32_dpp v193, v128 row_ror:1 row_mask:0xf bank_mask:0xf
	v_mov_b32_dpp v220, v128 row_ror:15 row_mask:0xf bank_mask:0xf
	v_mov_b32_dpp v175, v205 row_ror:1 row_mask:0xf bank_mask:0xf
	v_mov_b32_dpp v222, v203 row_ror:1 row_mask:0xf bank_mask:0xf
	v_mov_b32_dpp v223, v203 row_ror:15 row_mask:0xf bank_mask:0xf
	v_mov_b32_dpp v195, v129 row_ror:1 row_mask:0xf bank_mask:0xf
	v_mov_b32_dpp v225, v129 row_ror:15 row_mask:0xf bank_mask:0xf
	s_waitcnt vmcnt(0)
	v_pk_add_f32 v[120:121], v[150:151], v[120:121]
	v_mov_b32_dpp v239, v200 row_ror:1 row_mask:0xf bank_mask:0xf
	v_mov_b32_dpp v241, v108 row_ror:1 row_mask:0xf bank_mask:0xf
	v_mov_b32_dpp v242, v108 row_ror:15 row_mask:0xf bank_mask:0xf
	v_mov_b32_dpp v230, v130 row_ror:1 row_mask:0xf bank_mask:0xf
	v_mov_b32_dpp v245, v130 row_ror:15 row_mask:0xf bank_mask:0xf
	v_mov_b32_dpp v244, v201 row_ror:1 row_mask:0xf bank_mask:0xf
	v_mov_b32_dpp v247, v109 row_ror:1 row_mask:0xf bank_mask:0xf
	v_mov_b32_dpp v248, v109 row_ror:15 row_mask:0xf bank_mask:0xf
	v_mov_b32_dpp v236, v131 row_ror:1 row_mask:0xf bank_mask:0xf
	v_mov_b32_dpp v250, v131 row_ror:15 row_mask:0xf bank_mask:0xf
	v_pk_add_f32 v[122:123], v[152:153], v[122:123]
	s_mul_hi_i32 s23, s78, 0x5800
	s_mul_i32 s25, s78, 0x5800
	s_and_saveexec_b64 s[54:55], s[44:45]
	s_cbranch_execz .LBB0_1122
	s_add_u32 s68, s3, s25
	s_addc_u32 s69, s62, s23
	v_lshl_add_u64 v[160:161], v[170:171], 2, s[68:69]
	global_store_dwordx4 v[160:161], v[132:135], off nt
	s_nop 1
	v_add_co_u32_e32 v132, vcc, 0x5000, v160
	s_nop 1
	v_addc_co_u32_e32 v133, vcc, 0, v161, vcc
	global_store_dwordx4 v[132:133], v[120:123], off offset:2048 nt
	v_add_co_u32_e32 v132, vcc, 0xb000, v160
	s_nop 1
	v_addc_co_u32_e32 v133, vcc, 0, v161, vcc
	global_store_dwordx4 v[132:133], v[116:119], off nt

.LBB0_1124:
	s_or_b64 exec, exec, s[54:55]
	v_cndmask_b32_e64 v128, v107, v221, s[38:39]
	v_mul_f32_e32 v128, v146, v128
	v_cndmask_b32_e64 v129, v224, v173, s[40:41]
	v_fmac_f32_e32 v128, v204, v138
	v_fmac_f32_e32 v128, v142, v129
	v_cndmask_b32_e64 v107, v114, v107, s[38:39]
	v_add_f32_e32 v160, v150, v128
	v_cndmask_b32_e64 v128, v175, v240, s[38:39]
	v_mul_f32_e32 v107, v146, v107
	v_mul_f32_e32 v128, v147, v128
	v_cndmask_b32_e64 v114, v173, v220, s[40:41]
	v_fmac_f32_e32 v107, v202, v138
	v_cndmask_b32_e64 v129, v243, v223, s[40:41]
	v_fmac_f32_e32 v128, v205, v139
	v_fmac_f32_e32 v107, v142, v114
	v_cndmask_b32_e64 v114, v222, v175, s[38:39]
	v_fmac_f32_e32 v128, v143, v129
	v_mul_f32_e32 v114, v147, v114
	v_add_f32_e32 v161, v151, v128
	v_cndmask_b32_e64 v128, v223, v225, s[40:41]
	v_fmac_f32_e32 v114, v203, v139
	v_fmac_f32_e32 v114, v143, v128
	v_cndmask_b32_e64 v128, v239, v246, s[38:39]
	v_mul_f32_e32 v128, v148, v128
	v_cndmask_b32_e64 v129, v249, v242, s[40:41]
	v_fmac_f32_e32 v128, v200, v140
	v_fmac_f32_e32 v128, v144, v129
	v_add_f32_e32 v138, v152, v128
	v_cndmask_b32_e64 v128, v244, v251, s[38:39]
	v_mul_f32_e32 v128, v149, v128
	v_cndmask_b32_e64 v129, v252, v248, s[40:41]
	v_fmac_f32_e32 v128, v201, v141
	v_fmac_f32_e32 v128, v145, v129
	v_add_f32_e32 v139, v153, v128
	v_cndmask_b32_e64 v128, v241, v239, s[38:39]
	v_mul_f32_e32 v128, v148, v128
	v_cndmask_b32_e64 v129, v242, v245, s[40:41]
	v_fmac_f32_e32 v128, v108, v140
	v_cndmask_b32_e64 v108, v247, v244, s[38:39]
	v_fmac_f32_e32 v128, v144, v129
	v_mul_f32_e32 v108, v149, v108
	v_cvt_f32_i32_e32 v101, v101
	v_cvt_f32_i32_e32 v100, v100
	v_add_f32_e32 v140, v152, v128
	v_cndmask_b32_e64 v128, v248, v250, s[40:41]
	v_fmac_f32_e32 v108, v109, v141
	v_fmac_f32_e32 v108, v145, v128
	v_mov_b32_e32 v130, v194
	v_mov_b32_e32 v131, v194
	v_add_f32_e32 v141, v153, v108
	v_pk_mul_f32 v[108:109], v[132:133], v[130:131]
	v_mov_b32_e32 v134, v192
	v_mov_b32_e32 v135, v192
	v_pk_mul_f32 v[100:101], v[108:109], v[100:101]
	v_pk_mul_f32 v[108:109], v[132:133], v[134:135]
	v_mul_f32_e32 v132, 0xbfb8aa3b, v120
	v_cvt_f32_i32_e32 v97, v97
	v_cvt_f32_i32_e32 v96, v96
	v_exp_f32_e32 v132, v132
	v_mul_f32_e32 v133, 0xbfb8aa3b, v121
	v_cvt_f32_i32_e32 v99, v99
	v_cvt_f32_i32_e32 v98, v98
	v_exp_f32_e32 v133, v133
	v_pk_mul_f32 v[96:97], v[108:109], v[96:97]
	v_add_f32_e32 v108, 1.0, v132
	v_cvt_f32_i32_e32 v95, v95
	v_cvt_f32_i32_e32 v94, v94
	v_rcp_f32_e32 v132, v108
	v_mov_b32_e32 v195, v194
	v_mov_b32_e32 v193, v192
	v_pk_mul_f32 v[128:129], v[136:137], v[194:195]
	v_add_f32_e32 v108, 1.0, v133
	v_pk_mul_f32 v[98:99], v[128:129], v[98:99]
	v_pk_mul_f32 v[128:129], v[136:137], v[192:193]
	v_rcp_f32_e32 v133, v108
	v_pk_mul_f32 v[108:109], v[128:129], v[94:95]
	v_mul_f32_e32 v94, v120, v132
	v_mul_f32_e32 v94, v116, v94
	v_mul_f32_e32 v116, 0xbfb8aa3b, v122
	v_mul_f32_e32 v120, 0xbfb8aa3b, v123
	v_exp_f32_e32 v116, v116
	v_exp_f32_e32 v120, v120
	v_mul_f32_e32 v95, v121, v133
	v_mul_f32_e32 v95, v117, v95
	v_add_f32_e32 v116, 1.0, v116
	v_add_f32_e32 v117, 1.0, v120
	v_rcp_f32_e32 v116, v116
	v_rcp_f32_e32 v117, v117
	v_cvt_pk_bf16_f32 v94, v94, v95
	v_add_f32_e32 v107, v150, v107
	v_mul_f32_e32 v95, v122, v116
	v_mul_f32_e32 v116, v123, v117
	v_mul_f32_e32 v117, 0xbfb8aa3b, v160
	v_exp_f32_e32 v117, v117
	v_mul_f32_e32 v95, v118, v95
	v_mul_f32_e32 v118, 0xbfb8aa3b, v161
	v_exp_f32_e32 v118, v118
	v_add_f32_e32 v117, 1.0, v117
	v_rcp_f32_e32 v117, v117
	v_mul_f32_e32 v116, v119, v116
	v_add_f32_e32 v118, 1.0, v118
	v_rcp_f32_e32 v118, v118
	v_cvt_pk_bf16_f32 v95, v95, v116
	v_mul_f32_e32 v116, v160, v117
	v_mul_f32_e32 v117, 0xbfb8aa3b, v138
	v_exp_f32_e32 v117, v117
	v_mul_f32_e32 v98, v98, v116
	v_mul_f32_e32 v116, v161, v118
	v_mul_f32_e32 v118, 0xbfb8aa3b, v139
	v_exp_f32_e32 v118, v118
	v_mul_f32_e32 v99, v99, v116
	v_add_f32_e32 v116, 1.0, v117
	v_rcp_f32_e32 v116, v116
	v_add_f32_e32 v117, 1.0, v118
	v_rcp_f32_e32 v117, v117
	v_cvt_pk_bf16_f32 v98, v98, v99
	v_mul_f32_e32 v99, v138, v116
	v_mul_f32_e32 v116, 0xbfb8aa3b, v107
	v_exp_f32_e32 v116, v116
	v_mul_f32_e32 v99, v100, v99
	v_mul_f32_e32 v100, v139, v117
	v_mul_f32_e32 v100, v101, v100
	v_add_f32_e32 v101, 1.0, v116
	v_rcp_f32_e32 v101, v101
	v_add_f32_e32 v114, v151, v114
	v_mul_f32_e32 v117, 0xbfb8aa3b, v114
	v_exp_f32_e32 v117, v117
	v_cvt_pk_bf16_f32 v99, v99, v100
	v_mul_f32_e32 v100, v107, v101
	v_mul_f32_e32 v107, 0xbfb8aa3b, v140
	v_exp_f32_e32 v107, v107
	v_add_f32_e32 v116, 1.0, v117
	v_rcp_f32_e32 v116, v116
	v_mul_f32_e32 v100, v108, v100
	v_mul_f32_e32 v108, 0xbfb8aa3b, v141
	v_exp_f32_e32 v108, v108
	v_add_f32_e32 v107, 1.0, v107
	v_rcp_f32_e32 v107, v107
	v_mul_f32_e32 v101, v114, v116
	v_mul_f32_e32 v101, v109, v101
	v_add_f32_e32 v108, 1.0, v108
	v_rcp_f32_e32 v109, v108
	v_cvt_pk_bf16_f32 v108, v100, v101
	v_mul_f32_e32 v100, v140, v107
	v_mul_f32_e32 v101, 0xbfb8aa3b, v124
	v_mul_f32_e32 v107, 0xbfb8aa3b, v125
	v_exp_f32_e32 v101, v101
	v_exp_f32_e32 v107, v107
	v_mul_f32_e32 v96, v96, v100
	v_mul_f32_e32 v100, v141, v109
	v_mul_f32_e32 v97, v97, v100
	v_add_f32_e32 v100, 1.0, v101
	v_add_f32_e32 v101, 1.0, v107
	v_rcp_f32_e32 v100, v100
	v_rcp_f32_e32 v101, v101
	v_cvt_pk_bf16_f32 v109, v96, v97
	v_cvt_f32_i32_e32 v81, v81
	v_mul_f32_e32 v96, v124, v100
	v_mul_f32_e32 v97, v125, v101
	v_mul_f32_e32 v100, 0xbfb8aa3b, v126
	v_mul_f32_e32 v101, 0xbfb8aa3b, v127
	v_exp_f32_e32 v100, v100
	v_exp_f32_e32 v101, v101
	v_mul_f32_e32 v96, v110, v96
	v_mul_f32_e32 v97, v111, v97
	v_add_f32_e32 v100, 1.0, v100
	v_add_f32_e32 v101, 1.0, v101
	v_rcp_f32_e32 v100, v100
	v_rcp_f32_e32 v101, v101
	v_cvt_pk_bf16_f32 v116, v96, v97
	v_cvt_f32_i32_e32 v80, v80
	v_mul_f32_e32 v96, v126, v100
	v_mul_f32_e32 v97, v127, v101
	v_mul_f32_e32 v96, v112, v96
	v_mul_f32_e32 v97, v113, v97
	v_cvt_pk_bf16_f32 v117, v96, v97
	global_load_dwordx4 v[110:113], v[184:185], off offset:16
	global_load_dwordx4 v[126:129], v[182:183], off offset:16
	global_load_dwordx4 v[118:121], v[186:187], off offset:16
	global_load_dwordx4 v[122:125], v[188:189], off offset:16
	v_cvt_f32_i32_e32 v79, v79
	v_cvt_f32_i32_e32 v78, v78
	v_cvt_f32_i32_e32 v87, v87
	v_cvt_f32_i32_e32 v86, v86
	v_cvt_f32_i32_e32 v89, v89
	v_cvt_f32_i32_e32 v88, v88
	v_mul_f32_e32 v106, 0x3c010204, v106
	v_mov_b32_e32 v96, v198
	v_mov_b32_e32 v97, v198
	v_pk_mul_f32 v[96:97], v[106:107], v[96:97] op_sel_hi:[0,1]
	v_pk_mul_f32 v[100:101], v[106:107], v[198:199] op_sel_hi:[0,1]
	v_pk_mul_f32 v[80:81], v[96:97], v[80:81]
	v_mov_b32_e32 v96, v180
	v_mov_b32_e32 v97, v180
	v_pk_mul_f32 v[78:79], v[100:101], v[78:79]
	v_pk_mul_f32 v[100:101], v[96:97], v[130:131]
	v_pk_mul_f32 v[130:131], v[180:181], v[194:195]
	v_pk_mul_f32 v[100:101], v[100:101], v[88:89]
	v_pk_mul_f32 v[132:133], v[130:131], v[86:87]
	ds_read_b128 v[86:89], v213
	v_cvt_f32_i32_e32 v83, v83
	v_cvt_f32_i32_e32 v82, v82
	v_cvt_f32_i32_e32 v85, v85
	v_cvt_f32_i32_e32 v84, v84
	v_pk_mul_f32 v[96:97], v[96:97], v[134:135]
	v_pk_mul_f32 v[130:131], v[180:181], v[192:193]
	v_pk_mul_f32 v[96:97], v[96:97], v[84:85]
	v_pk_mul_f32 v[130:131], v[130:131], v[82:83]
	ds_read_b128 v[82:85], v212 offset:1040
	s_waitcnt lgkmcnt(1)
	v_pk_mul_f32 v[134:135], v[88:89], 0 op_sel_hi:[1,0]
	v_pk_mul_f32 v[138:139], v[86:87], 0 op_sel_hi:[1,0]
	v_cndmask_b32_e64 v86, v86, v138, s[36:37]
	v_cndmask_b32_e64 v87, v87, v139, s[36:37]
	v_cndmask_b32_e64 v107, v88, v134, s[36:37]
	v_cndmask_b32_e64 v205, v89, v135, s[36:37]
	v_mov_b32_dpp v140, v102 row_ror:1 row_mask:0xf bank_mask:0xf
	v_mov_b32_dpp v146, v103 row_ror:1 row_mask:0xf bank_mask:0xf
	v_mov_b32_dpp v88, v102 row_ror:15 row_mask:0xf bank_mask:0xf
	v_mov_b32_dpp v143, v132 row_ror:15 row_mask:0xf bank_mask:0xf
	v_mov_b32_dpp v89, v103 row_ror:15 row_mask:0xf bank_mask:0xf
	v_mov_b32_dpp v149, v133 row_ror:15 row_mask:0xf bank_mask:0xf
	v_cndmask_b32_e64 v87, v146, v87, s[38:39]
	v_cndmask_b32_e64 v86, v140, v86, s[38:39]
	v_cndmask_b32_e64 v89, v89, v149, s[40:41]
	v_cndmask_b32_e64 v88, v88, v143, s[40:41]
	v_mov_b32_dpp v152, v104 row_ror:1 row_mask:0xf bank_mask:0xf
	v_mov_b32_dpp v199, v105 row_ror:1 row_mask:0xf bank_mask:0xf
	v_mov_b32_dpp v220, v104 row_ror:15 row_mask:0xf bank_mask:0xf
	v_mov_b32_dpp v175, v100 row_ror:15 row_mask:0xf bank_mask:0xf
	v_mov_b32_dpp v221, v105 row_ror:15 row_mask:0xf bank_mask:0xf
	v_mov_b32_dpp v200, v101 row_ror:15 row_mask:0xf bank_mask:0xf
	v_cndmask_b32_e64 v221, v221, v200, s[40:41]
	v_cndmask_b32_e64 v220, v220, v175, s[40:41]
	s_waitcnt vmcnt(3)
	v_pk_mul_f32 v[150:151], v[102:103], v[110:111]
	v_pk_mul_f32 v[160:161], v[104:105], v[112:113]
	s_waitcnt vmcnt(2)
	v_pk_fma_f32 v[86:87], v[126:127], v[86:87], v[150:151]
	s_waitcnt vmcnt(1)
	v_pk_fma_f32 v[86:87], v[118:119], v[88:89], v[86:87]
	v_cndmask_b32_e64 v89, v199, v205, s[38:39]
	v_cndmask_b32_e64 v88, v152, v107, s[38:39]
	v_pk_fma_f32 v[88:89], v[128:129], v[88:89], v[160:161]
	v_pk_fma_f32 v[88:89], v[120:121], v[220:221], v[88:89]
	v_mov_b32_dpp v114, v132 row_ror:1 row_mask:0xf bank_mask:0xf
	v_mov_b32_dpp v134, v130 row_ror:1 row_mask:0xf bank_mask:0xf
	v_mov_b32_dpp v135, v130 row_ror:15 row_mask:0xf bank_mask:0xf
	v_mov_b32_dpp v201, v90 row_ror:1 row_mask:0xf bank_mask:0xf
	v_mov_b32_dpp v139, v90 row_ror:15 row_mask:0xf bank_mask:0xf
	v_mov_b32_dpp v138, v133 row_ror:1 row_mask:0xf bank_mask:0xf
	v_mov_b32_dpp v141, v131 row_ror:1 row_mask:0xf bank_mask:0xf
	v_mov_b32_dpp v142, v131 row_ror:15 row_mask:0xf bank_mask:0xf
	v_mov_b32_dpp v202, v91 row_ror:1 row_mask:0xf bank_mask:0xf
	v_mov_b32_dpp v144, v91 row_ror:15 row_mask:0xf bank_mask:0xf
	s_waitcnt vmcnt(0)
	v_pk_add_f32 v[86:87], v[122:123], v[86:87]
	v_mov_b32_dpp v145, v100 row_ror:1 row_mask:0xf bank_mask:0xf
	v_mov_b32_dpp v147, v96 row_ror:1 row_mask:0xf bank_mask:0xf
	v_mov_b32_dpp v148, v96 row_ror:15 row_mask:0xf bank_mask:0xf
	v_mov_b32_dpp v203, v92 row_ror:1 row_mask:0xf bank_mask:0xf
	v_mov_b32_dpp v151, v92 row_ror:15 row_mask:0xf bank_mask:0xf
	v_mov_b32_dpp v150, v101 row_ror:1 row_mask:0xf bank_mask:0xf
	v_mov_b32_dpp v153, v97 row_ror:1 row_mask:0xf bank_mask:0xf
	v_mov_b32_dpp v173, v97 row_ror:15 row_mask:0xf bank_mask:0xf
	v_mov_b32_dpp v204, v93 row_ror:1 row_mask:0xf bank_mask:0xf
	v_mov_b32_dpp v198, v93 row_ror:15 row_mask:0xf bank_mask:0xf
	v_pk_add_f32 v[88:89], v[124:125], v[88:89]
	s_and_saveexec_b64 s[54:55], s[44:45]
	s_cbranch_execz .LBB0_1126
	s_add_u32 s68, s3, s25
	s_addc_u32 s69, s62, s23
	v_lshl_add_u64 v[160:161], v[170:171], 2, s[68:69]
	global_store_dwordx4 v[160:161], v[102:105], off offset:16 nt
	s_nop 1
	v_add_co_u32_e32 v102, vcc, 0x5000, v160
	s_nop 1
	v_addc_co_u32_e32 v103, vcc, 0, v161, vcc
	global_store_dwordx4 v[102:103], v[86:89], off offset:2064 nt
	v_add_co_u32_e32 v102, vcc, 0xb000, v160
	s_nop 1
	v_addc_co_u32_e32 v103, vcc, 0, v161, vcc
	global_store_dwordx4 v[102:103], v[78:81], off offset:16 nt

.LBB0_1128:
	s_or_b64 exec, exec, s[54:55]
	v_cndmask_b32_e64 v90, v114, v140, s[38:39]
	v_mul_f32_e32 v90, v126, v90
	v_cndmask_b32_e64 v91, v143, v135, s[40:41]
	v_fmac_f32_e32 v90, v132, v110
	v_fmac_f32_e32 v90, v118, v91
	v_add_f32_e32 v104, v122, v90
	v_cndmask_b32_e64 v90, v138, v146, s[38:39]
	v_mul_f32_e32 v90, v127, v90
	v_cndmask_b32_e64 v91, v149, v142, s[40:41]
	v_fmac_f32_e32 v90, v133, v111
	v_fmac_f32_e32 v90, v119, v91
	v_add_f32_e32 v105, v123, v90
	v_cndmask_b32_e64 v90, v134, v114, s[38:39]
	v_mul_f32_e32 v90, v126, v90
	v_cndmask_b32_e64 v91, v135, v139, s[40:41]
	v_fmac_f32_e32 v90, v130, v110
	v_fmac_f32_e32 v90, v118, v91
	v_add_f32_e32 v110, v122, v90
	v_cndmask_b32_e64 v90, v141, v138, s[38:39]
	v_mul_f32_e32 v90, v127, v90
	v_cndmask_b32_e64 v91, v142, v144, s[40:41]
	v_fmac_f32_e32 v90, v131, v111
	v_cvt_f32_i32_e32 v69, v69
	v_cvt_f32_i32_e32 v68, v68
	v_fmac_f32_e32 v90, v119, v91
	v_add_f32_e32 v111, v123, v90
	v_cndmask_b32_e64 v90, v145, v152, s[38:39]
	v_mov_b32_e32 v92, v194
	v_mov_b32_e32 v93, v194
	v_mul_f32_e32 v90, v128, v90
	v_pk_mul_f32 v[92:93], v[102:103], v[92:93]
	v_fmac_f32_e32 v90, v100, v112
	v_pk_mul_f32 v[68:69], v[92:93], v[68:69]
	v_mov_b32_e32 v92, v192
	v_mov_b32_e32 v93, v192
	v_mul_f32_e32 v100, 0xbfb8aa3b, v86
	v_cvt_f32_i32_e32 v61, v61
	v_cvt_f32_i32_e32 v60, v60
	v_pk_mul_f32 v[92:93], v[102:103], v[92:93]
	v_exp_f32_e32 v100, v100
	v_mul_f32_e32 v102, 0xbfb8aa3b, v87
	v_exp_f32_e32 v102, v102
	v_pk_mul_f32 v[60:61], v[92:93], v[60:61]
	v_add_f32_e32 v92, 1.0, v100
	v_rcp_f32_e32 v92, v92
	v_add_f32_e32 v93, 1.0, v102
	v_cndmask_b32_e64 v91, v175, v148, s[40:41]
	v_rcp_f32_e32 v93, v93
	v_fmac_f32_e32 v90, v120, v91
	v_add_f32_e32 v118, v124, v90
	v_cndmask_b32_e64 v90, v150, v199, s[38:39]
	v_mul_f32_e32 v90, v129, v90
	v_mul_f32_e32 v86, v86, v92
	v_cndmask_b32_e64 v91, v200, v173, s[40:41]
	v_fmac_f32_e32 v90, v101, v113
	v_mul_f32_e32 v78, v78, v86
	v_mul_f32_e32 v86, v87, v93
	v_mul_f32_e32 v87, 0xbfb8aa3b, v88
	v_fmac_f32_e32 v90, v121, v91
	v_exp_f32_e32 v87, v87
	v_add_f32_e32 v101, v125, v90
	v_cndmask_b32_e64 v90, v147, v145, s[38:39]
	v_mul_f32_e32 v90, v128, v90
	v_cndmask_b32_e64 v91, v148, v151, s[40:41]
	v_fmac_f32_e32 v90, v96, v112
	v_fmac_f32_e32 v90, v120, v91
	v_cvt_f32_i32_e32 v67, v67
	v_cvt_f32_i32_e32 v66, v66
	v_mul_f32_e32 v79, v79, v86
	v_add_f32_e32 v86, 1.0, v87
	v_add_f32_e32 v112, v124, v90
	v_cndmask_b32_e64 v90, v153, v150, s[38:39]
	v_cvt_f32_i32_e32 v59, v59
	v_cvt_f32_i32_e32 v58, v58
	v_mul_f32_e32 v92, 0xbfb8aa3b, v89
	v_rcp_f32_e32 v86, v86
	v_mul_f32_e32 v90, v129, v90
	v_exp_f32_e32 v92, v92
	v_fmac_f32_e32 v90, v97, v113
	v_pk_mul_f32 v[96:97], v[106:107], v[194:195]
	v_cndmask_b32_e64 v91, v173, v198, s[40:41]
	v_pk_mul_f32 v[66:67], v[96:97], v[66:67]
	v_pk_mul_f32 v[96:97], v[106:107], v[192:193]
	v_add_f32_e32 v87, 1.0, v92
	v_pk_mul_f32 v[58:59], v[96:97], v[58:59]
	v_cvt_pk_bf16_f32 v96, v78, v79
	v_mul_f32_e32 v78, v88, v86
	v_mul_f32_e32 v78, v80, v78
	v_mul_f32_e32 v80, 0xbfb8aa3b, v104
	v_rcp_f32_e32 v87, v87
	v_exp_f32_e32 v80, v80
	v_mul_f32_e32 v86, 0xbfb8aa3b, v105
	v_exp_f32_e32 v86, v86
	v_mul_f32_e32 v79, v89, v87
	v_add_f32_e32 v80, 1.0, v80
	v_mul_f32_e32 v79, v81, v79
	v_rcp_f32_e32 v80, v80
	v_add_f32_e32 v81, 1.0, v86
	v_rcp_f32_e32 v81, v81
	v_cvt_pk_bf16_f32 v97, v78, v79
	v_mul_f32_e32 v79, 0xbfb8aa3b, v118
	v_exp_f32_e32 v79, v79
	v_mul_f32_e32 v78, v104, v80
	v_mul_f32_e32 v66, v66, v78
	v_mul_f32_e32 v78, v105, v81
	v_mul_f32_e32 v67, v67, v78
	v_add_f32_e32 v78, 1.0, v79
	v_mul_f32_e32 v80, 0xbfb8aa3b, v101
	v_rcp_f32_e32 v78, v78
	v_exp_f32_e32 v80, v80
	v_cvt_pk_bf16_f32 v100, v66, v67
	v_fmac_f32_e32 v90, v121, v91
	v_mul_f32_e32 v66, v118, v78
	v_add_f32_e32 v79, 1.0, v80
	v_mul_f32_e32 v66, v68, v66
	v_mul_f32_e32 v68, 0xbfb8aa3b, v110
	v_rcp_f32_e32 v79, v79
	v_exp_f32_e32 v68, v68
	v_mul_f32_e32 v78, 0xbfb8aa3b, v111
	v_exp_f32_e32 v78, v78
	v_mul_f32_e32 v67, v101, v79
	v_add_f32_e32 v68, 1.0, v68
	v_mul_f32_e32 v67, v69, v67
	v_rcp_f32_e32 v68, v68
	v_add_f32_e32 v69, 1.0, v78
	v_rcp_f32_e32 v69, v69
	v_cvt_pk_bf16_f32 v101, v66, v67
	v_mul_f32_e32 v67, 0xbfb8aa3b, v112
	v_exp_f32_e32 v67, v67
	v_mul_f32_e32 v66, v110, v68
	v_mul_f32_e32 v58, v58, v66
	v_mul_f32_e32 v66, v111, v69
	v_add_f32_e32 v113, v125, v90
	v_mul_f32_e32 v59, v59, v66
	v_add_f32_e32 v66, 1.0, v67
	v_mul_f32_e32 v68, 0xbfb8aa3b, v113
	v_rcp_f32_e32 v66, v66
	v_exp_f32_e32 v68, v68
	v_cvt_pk_bf16_f32 v110, v58, v59
	s_lshl_b32 s0, s76, 7
	v_mul_f32_e32 v58, v112, v66
	v_add_f32_e32 v67, 1.0, v68
	v_mul_f32_e32 v58, v60, v58
	v_mul_f32_e32 v60, 0xbfb8aa3b, v82
	v_rcp_f32_e32 v67, v67
	v_exp_f32_e32 v60, v60
	v_mul_f32_e32 v66, 0xbfb8aa3b, v83
	v_exp_f32_e32 v66, v66
	v_mul_f32_e32 v59, v113, v67
	v_add_f32_e32 v60, 1.0, v60
	v_mul_f32_e32 v59, v61, v59
	v_rcp_f32_e32 v60, v60
	v_add_f32_e32 v61, 1.0, v66
	v_rcp_f32_e32 v61, v61
	v_cvt_pk_bf16_f32 v111, v58, v59
	v_mul_f32_e32 v58, v82, v60
	v_mul_f32_e32 v60, 0xbfb8aa3b, v84
	v_mul_f32_e32 v59, v83, v61
	v_exp_f32_e32 v60, v60
	v_mul_f32_e32 v61, 0xbfb8aa3b, v85
	v_exp_f32_e32 v61, v61
	s_mul_i32 s1, s76, 0x2c0000
	v_add_f32_e32 v60, 1.0, v60
	v_rcp_f32_e32 v60, v60
	v_add_f32_e32 v61, 1.0, v61
	v_rcp_f32_e32 v61, v61
	s_mul_hi_i32 s0, s0, 0x5800
	s_add_u32 s54, s64, s1
	v_lshl_add_u32 v90, s74, 8, v217
	v_mul_f32_e32 v58, v74, v58
	s_addc_u32 s55, s57, s0
	v_or_b32_e32 v114, v90, v218
	v_mul_f32_e32 v59, v75, v59
	v_cvt_pk_bf16_f32 v118, v58, v59
	v_mul_f32_e32 v58, v84, v60
	v_lshl_add_u64 v[90:91], v[114:115], 1, s[54:55]
	v_mul_f32_e32 v58, v76, v58
	v_mul_f32_e32 v59, v85, v61
	s_mov_b32 s0, 0x2c000
	v_mul_f32_e32 v59, v77, v59
	v_cvt_pk_bf16_f32 v119, v58, v59
	v_add_co_u32_e32 v58, vcc, s0, v90
	s_mov_b32 s0, 0x58000
	s_nop 0
	v_addc_co_u32_e32 v59, vcc, 0, v91, vcc
	global_store_dwordx4 v[58:59], v[98:101], off nt
	v_add_co_u32_e32 v58, vcc, s0, v90
	s_mov_b32 s0, 0x84000
	s_nop 0
	v_addc_co_u32_e32 v59, vcc, 0, v91, vcc
	global_store_dwordx4 v[58:59], v[108:111], off nt
	v_add_co_u32_e32 v58, vcc, s0, v90
	global_store_dwordx4 v[90:91], v[94:97], off nt
	s_nop 0
	v_addc_co_u32_e32 v59, vcc, 0, v91, vcc
	global_store_dwordx4 v[58:59], v[116:119], off nt
	global_load_dwordx4 v[66:69], v[184:185], off
	global_load_dwordx4 v[82:85], v[182:183], off
	global_load_dwordx4 v[74:77], v[186:187], off
	global_load_dwordx4 v[78:81], v[188:189], off
	v_cvt_f32_i32_e32 v49, v49
	v_cvt_f32_i32_e32 v48, v48
	v_cvt_f32_i32_e32 v47, v47
	v_cvt_f32_i32_e32 v46, v46
	v_cvt_f32_i32_e32 v55, v55
	v_cvt_f32_i32_e32 v54, v54
	v_cvt_f32_i32_e32 v57, v57
	v_cvt_f32_i32_e32 v56, v56
	v_mov_b32_e32 v60, v178
	v_mov_b32_e32 v61, v178
	v_mov_b32_e32 v58, v136
	v_mov_b32_e32 v59, v136
	v_pk_mul_f32 v[60:61], v[58:59], v[60:61]
	v_pk_mul_f32 v[86:87], v[136:137], v[178:179]
	v_pk_mul_f32 v[48:49], v[60:61], v[48:49]
	v_mov_b32_e32 v60, v190
	v_mov_b32_e32 v61, v190
	v_pk_mul_f32 v[46:47], v[86:87], v[46:47]
	v_pk_mul_f32 v[86:87], v[60:61], v[174:175] op_sel_hi:[1,0]
	v_pk_mul_f32 v[92:93], v[190:191], v[174:175] op_sel_hi:[1,0]
	v_pk_mul_f32 v[88:89], v[86:87], v[56:57]
	v_pk_mul_f32 v[94:95], v[92:93], v[54:55]
	ds_read_b128 v[54:57], v214
	v_cvt_f32_i32_e32 v51, v51
	v_cvt_f32_i32_e32 v50, v50
	v_cvt_f32_i32_e32 v53, v53
	v_cvt_f32_i32_e32 v52, v52
	v_pk_mul_f32 v[60:61], v[60:61], v[172:173] op_sel_hi:[1,0]
	v_pk_mul_f32 v[92:93], v[190:191], v[172:173] op_sel_hi:[1,0]
	v_pk_mul_f32 v[86:87], v[60:61], v[52:53]
	v_pk_mul_f32 v[92:93], v[92:93], v[50:51]
	ds_read_b128 v[50:53], v215 offset:1024
	s_waitcnt lgkmcnt(1)
	v_pk_mul_f32 v[60:61], v[56:57], 0 op_sel_hi:[1,0]
	v_pk_mul_f32 v[96:97], v[54:55], 0 op_sel_hi:[1,0]
	v_cndmask_b32_e64 v54, v54, v96, s[46:47]
	v_cndmask_b32_e64 v55, v55, v97, s[46:47]
	v_cndmask_b32_e64 v125, v56, v60, s[46:47]
	v_cndmask_b32_e64 v128, v57, v61, s[46:47]
	v_mov_b32_dpp v101, v70 row_ror:1 row_mask:0xf bank_mask:0xf
	v_mov_b32_dpp v109, v71 row_ror:1 row_mask:0xf bank_mask:0xf
	v_mov_b32_dpp v56, v70 row_ror:15 row_mask:0xf bank_mask:0xf
	v_mov_b32_dpp v104, v94 row_ror:15 row_mask:0xf bank_mask:0xf
	v_mov_b32_dpp v57, v71 row_ror:15 row_mask:0xf bank_mask:0xf
	v_mov_b32_dpp v112, v95 row_ror:15 row_mask:0xf bank_mask:0xf
	v_cndmask_b32_e64 v55, v109, v55, s[38:39]
	v_cndmask_b32_e64 v54, v101, v54, s[38:39]
	v_cndmask_b32_e64 v57, v57, v112, s[40:41]
	v_cndmask_b32_e64 v56, v56, v104, s[40:41]
	v_mov_b32_dpp v116, v72 row_ror:1 row_mask:0xf bank_mask:0xf
	v_mov_b32_dpp v121, v73 row_ror:1 row_mask:0xf bank_mask:0xf
	v_mov_b32_dpp v130, v72 row_ror:15 row_mask:0xf bank_mask:0xf
	v_mov_b32_dpp v119, v88 row_ror:15 row_mask:0xf bank_mask:0xf
	v_mov_b32_dpp v129, v73 row_ror:15 row_mask:0xf bank_mask:0xf
	v_mov_b32_dpp v122, v89 row_ror:15 row_mask:0xf bank_mask:0xf
	v_cndmask_b32_e64 v129, v129, v122, s[40:41]
	s_waitcnt vmcnt(3)
	v_pk_mul_f32 v[110:111], v[70:71], v[66:67]
	v_pk_mul_f32 v[126:127], v[72:73], v[68:69]
	s_waitcnt vmcnt(2)
	v_pk_fma_f32 v[54:55], v[82:83], v[54:55], v[110:111]
	s_waitcnt vmcnt(1)
	v_pk_fma_f32 v[54:55], v[74:75], v[56:57], v[54:55]
	v_cndmask_b32_e64 v57, v121, v128, s[38:39]
	v_cndmask_b32_e64 v56, v116, v125, s[38:39]
	v_cndmask_b32_e64 v128, v130, v119, s[40:41]
	v_pk_fma_f32 v[56:57], v[84:85], v[56:57], v[126:127]
	v_pk_fma_f32 v[56:57], v[76:77], v[128:129], v[56:57]
	v_mov_b32_dpp v96, v94 row_ror:1 row_mask:0xf bank_mask:0xf
	v_mov_b32_dpp v97, v92 row_ror:1 row_mask:0xf bank_mask:0xf
	v_mov_b32_dpp v98, v92 row_ror:15 row_mask:0xf bank_mask:0xf
	v_mov_b32_dpp v60, v62 row_ror:1 row_mask:0xf bank_mask:0xf
	v_mov_b32_dpp v100, v62 row_ror:15 row_mask:0xf bank_mask:0xf
	v_mov_b32_dpp v99, v95 row_ror:1 row_mask:0xf bank_mask:0xf
	v_mov_b32_dpp v102, v93 row_ror:1 row_mask:0xf bank_mask:0xf
	v_mov_b32_dpp v103, v93 row_ror:15 row_mask:0xf bank_mask:0xf
	v_mov_b32_dpp v61, v63 row_ror:1 row_mask:0xf bank_mask:0xf
	v_mov_b32_dpp v105, v63 row_ror:15 row_mask:0xf bank_mask:0xf
	s_waitcnt vmcnt(0)
	v_pk_add_f32 v[54:55], v[78:79], v[54:55]
	v_mov_b32_dpp v108, v88 row_ror:1 row_mask:0xf bank_mask:0xf
	v_mov_b32_dpp v110, v86 row_ror:1 row_mask:0xf bank_mask:0xf
	v_mov_b32_dpp v111, v86 row_ror:15 row_mask:0xf bank_mask:0xf
	v_mov_b32_dpp v123, v64 row_ror:1 row_mask:0xf bank_mask:0xf
	v_mov_b32_dpp v114, v64 row_ror:15 row_mask:0xf bank_mask:0xf
	v_mov_b32_dpp v113, v89 row_ror:1 row_mask:0xf bank_mask:0xf
	v_mov_b32_dpp v117, v87 row_ror:1 row_mask:0xf bank_mask:0xf
	v_mov_b32_dpp v118, v87 row_ror:15 row_mask:0xf bank_mask:0xf
	v_mov_b32_dpp v124, v65 row_ror:1 row_mask:0xf bank_mask:0xf
	v_mov_b32_dpp v120, v65 row_ror:15 row_mask:0xf bank_mask:0xf
	v_pk_add_f32 v[56:57], v[80:81], v[56:57]
	s_and_saveexec_b64 s[54:55], s[50:51]
	s_cbranch_execz .LBB0_1130
	s_add_u32 s68, s3, s25
	s_addc_u32 s69, s62, s23
	v_lshl_add_u64 v[126:127], v[170:171], 2, s[68:69]
	global_store_dwordx4 v[126:127], v[70:73], off nt
	s_nop 1
	v_add_co_u32_e32 v70, vcc, 0x5000, v126
	s_nop 1
	v_addc_co_u32_e32 v71, vcc, 0, v127, vcc
	global_store_dwordx4 v[70:71], v[54:57], off offset:2048 nt
	v_add_co_u32_e32 v70, vcc, 0xb000, v126
	s_nop 1
	v_addc_co_u32_e32 v71, vcc, 0, v127, vcc
	global_store_dwordx4 v[70:71], v[46:49], off nt

.LBB0_1132:
	s_or_b64 exec, exec, s[54:55]
	v_cndmask_b32_e64 v38, v96, v101, s[38:39]
	v_mul_f32_e32 v38, v82, v38
	v_cndmask_b32_e64 v39, v104, v98, s[40:41]
	v_fmac_f32_e32 v38, v94, v66
	v_fmac_f32_e32 v38, v74, v39
	v_add_f32_e32 v70, v78, v38
	v_cndmask_b32_e64 v38, v99, v109, s[38:39]
	v_mul_f32_e32 v38, v83, v38
	v_cndmask_b32_e64 v39, v112, v103, s[40:41]
	v_fmac_f32_e32 v38, v95, v67
	v_fmac_f32_e32 v38, v75, v39
	v_add_f32_e32 v71, v79, v38
	v_cndmask_b32_e64 v38, v97, v96, s[38:39]
	v_mul_f32_e32 v38, v82, v38
	v_cndmask_b32_e64 v39, v98, v100, s[40:41]
	v_fmac_f32_e32 v38, v92, v66
	v_fmac_f32_e32 v38, v74, v39
	v_add_f32_e32 v66, v78, v38
	v_cndmask_b32_e64 v38, v102, v99, s[38:39]
	v_mul_f32_e32 v38, v83, v38
	v_cndmask_b32_e64 v39, v103, v105, s[40:41]
	v_fmac_f32_e32 v38, v93, v67
	v_fmac_f32_e32 v38, v75, v39
	v_add_f32_e32 v67, v79, v38
	v_cndmask_b32_e64 v38, v108, v116, s[38:39]
	v_mul_f32_e32 v38, v84, v38
	v_cndmask_b32_e64 v39, v119, v111, s[40:41]
	v_fmac_f32_e32 v38, v88, v68
	v_fmac_f32_e32 v38, v76, v39
	v_add_f32_e32 v72, v80, v38
	v_cndmask_b32_e64 v38, v113, v121, s[38:39]
	v_mul_f32_e32 v38, v85, v38
	v_cndmask_b32_e64 v39, v122, v118, s[40:41]
	v_fmac_f32_e32 v38, v89, v69
	v_fmac_f32_e32 v38, v77, v39
	v_add_f32_e32 v73, v81, v38
	v_cndmask_b32_e64 v38, v110, v108, s[38:39]
	v_mul_f32_e32 v38, v84, v38
	v_cndmask_b32_e64 v39, v111, v114, s[40:41]
	v_fmac_f32_e32 v38, v86, v68
	v_fmac_f32_e32 v38, v76, v39
	v_add_f32_e32 v68, v80, v38
	v_cndmask_b32_e64 v38, v117, v113, s[38:39]
	v_cvt_f32_i32_e32 v31, v31
	v_cvt_f32_i32_e32 v30, v30
	v_mul_f32_e32 v38, v85, v38
	v_mul_f32_e32 v74, 0xbfb8aa3b, v54
	v_mov_b32_e32 v175, v174
	v_cndmask_b32_e64 v39, v118, v120, s[40:41]
	v_fmac_f32_e32 v38, v87, v69
	v_cvt_f32_i32_e32 v29, v29
	v_cvt_f32_i32_e32 v28, v28
	v_exp_f32_e32 v74, v74
	v_fmac_f32_e32 v38, v77, v39
	v_pk_mul_f32 v[64:65], v[136:137], v[174:175]
	v_add_f32_e32 v69, v81, v38
	v_mov_b32_e32 v40, v174
	v_mov_b32_e32 v41, v174
	v_mov_b32_e32 v38, v136
	v_mov_b32_e32 v39, v136
	v_pk_mul_f32 v[30:31], v[64:65], v[30:31]
	v_mov_b32_e32 v64, v172
	v_mov_b32_e32 v65, v172
	v_pk_mul_f32 v[62:63], v[38:39], v[40:41]
	v_pk_mul_f32 v[38:39], v[38:39], v[64:65]
	v_mul_f32_e32 v75, 0xbfb8aa3b, v55
	v_cvt_f32_i32_e32 v33, v33
	v_cvt_f32_i32_e32 v32, v32
	v_exp_f32_e32 v75, v75
	v_pk_mul_f32 v[28:29], v[38:39], v[28:29]
	v_add_f32_e32 v38, 1.0, v74
	v_cvt_f32_i32_e32 v27, v27
	v_cvt_f32_i32_e32 v26, v26
	v_rcp_f32_e32 v74, v38
	v_mov_b32_e32 v173, v172
	v_pk_mul_f32 v[32:33], v[62:63], v[32:33]
	v_pk_mul_f32 v[62:63], v[136:137], v[172:173]
	v_add_f32_e32 v38, 1.0, v75
	v_rcp_f32_e32 v75, v38
	v_pk_mul_f32 v[38:39], v[62:63], v[26:27]
	v_mul_f32_e32 v26, v54, v74
	v_mul_f32_e32 v26, v46, v26
	v_mul_f32_e32 v46, 0xbfb8aa3b, v56
	v_mul_f32_e32 v54, 0xbfb8aa3b, v57
	v_exp_f32_e32 v46, v46
	v_exp_f32_e32 v54, v54
	v_mul_f32_e32 v27, v55, v75
	v_mul_f32_e32 v27, v47, v27
	v_add_f32_e32 v46, 1.0, v46
	v_add_f32_e32 v47, 1.0, v54
	v_rcp_f32_e32 v46, v46
	v_rcp_f32_e32 v47, v47
	v_cvt_pk_bf16_f32 v26, v26, v27
	v_cvt_f32_i32_e32 v17, v17
	v_mul_f32_e32 v27, v56, v46
	v_mul_f32_e32 v46, v57, v47
	v_mul_f32_e32 v47, 0xbfb8aa3b, v70
	v_exp_f32_e32 v47, v47
	v_mul_f32_e32 v27, v48, v27
	v_mul_f32_e32 v48, 0xbfb8aa3b, v71
	v_exp_f32_e32 v48, v48
	v_add_f32_e32 v47, 1.0, v47
	v_rcp_f32_e32 v47, v47
	v_mul_f32_e32 v46, v49, v46
	v_add_f32_e32 v48, 1.0, v48
	v_rcp_f32_e32 v48, v48
	v_cvt_pk_bf16_f32 v27, v27, v46
	v_mul_f32_e32 v46, v70, v47
	v_mul_f32_e32 v47, 0xbfb8aa3b, v72
	v_exp_f32_e32 v47, v47
	v_mul_f32_e32 v30, v30, v46
	v_mul_f32_e32 v46, v71, v48
	v_mul_f32_e32 v48, 0xbfb8aa3b, v73
	v_exp_f32_e32 v48, v48
	v_mul_f32_e32 v31, v31, v46
	v_add_f32_e32 v46, 1.0, v47
	v_rcp_f32_e32 v46, v46
	v_add_f32_e32 v47, 1.0, v48
	v_rcp_f32_e32 v47, v47
	v_cvt_pk_bf16_f32 v30, v30, v31
	v_mul_f32_e32 v31, v72, v46
	v_mul_f32_e32 v46, 0xbfb8aa3b, v66
	v_exp_f32_e32 v46, v46
	v_mul_f32_e32 v31, v32, v31
	v_mul_f32_e32 v32, v73, v47
	v_mul_f32_e32 v47, 0xbfb8aa3b, v67
	v_mul_f32_e32 v32, v33, v32
	v_add_f32_e32 v33, 1.0, v46
	v_exp_f32_e32 v47, v47
	v_rcp_f32_e32 v33, v33
	v_cvt_pk_bf16_f32 v31, v31, v32
	v_cvt_f32_i32_e32 v16, v16
	v_add_f32_e32 v46, 1.0, v47
	v_mul_f32_e32 v32, v66, v33
	v_rcp_f32_e32 v46, v46
	v_mul_f32_e32 v32, v38, v32
	v_mul_f32_e32 v38, 0xbfb8aa3b, v68
	v_exp_f32_e32 v38, v38
	v_mul_f32_e32 v33, v67, v46
	v_mul_f32_e32 v46, 0xbfb8aa3b, v69
	v_exp_f32_e32 v46, v46
	v_add_f32_e32 v38, 1.0, v38
	v_mul_f32_e32 v33, v39, v33
	v_rcp_f32_e32 v39, v38
	v_add_f32_e32 v38, 1.0, v46
	v_rcp_f32_e32 v46, v38
	v_cvt_pk_bf16_f32 v38, v32, v33
	v_mul_f32_e32 v32, v68, v39
	v_mul_f32_e32 v33, 0xbfb8aa3b, v50
	v_mul_f32_e32 v39, 0xbfb8aa3b, v51
	v_exp_f32_e32 v33, v33
	v_exp_f32_e32 v39, v39
	v_mul_f32_e32 v28, v28, v32
	v_mul_f32_e32 v32, v69, v46
	v_mul_f32_e32 v29, v29, v32
	v_add_f32_e32 v32, 1.0, v33
	v_add_f32_e32 v33, 1.0, v39
	v_rcp_f32_e32 v32, v32
	v_rcp_f32_e32 v33, v33
	v_cvt_pk_bf16_f32 v39, v28, v29
	v_cvt_f32_i32_e32 v23, v23
	v_mul_f32_e32 v28, v50, v32
	v_mul_f32_e32 v29, v51, v33
	v_mul_f32_e32 v32, 0xbfb8aa3b, v52
	v_mul_f32_e32 v33, 0xbfb8aa3b, v53
	v_exp_f32_e32 v32, v32
	v_exp_f32_e32 v33, v33
	v_mul_f32_e32 v28, v58, v28
	v_mul_f32_e32 v29, v59, v29
	v_add_f32_e32 v32, 1.0, v32
	v_add_f32_e32 v33, 1.0, v33
	v_rcp_f32_e32 v32, v32
	v_rcp_f32_e32 v33, v33
	v_cvt_pk_bf16_f32 v46, v28, v29
	v_cvt_f32_i32_e32 v22, v22
	v_mul_f32_e32 v28, v52, v32
	v_mul_f32_e32 v29, v53, v33
	v_mul_f32_e32 v28, v60, v28
	v_mul_f32_e32 v29, v61, v29
	v_cvt_pk_bf16_f32 v47, v28, v29
	global_load_dwordx4 v[56:59], v[184:185], off offset:16
	global_load_dwordx4 v[60:63], v[182:183], off offset:16
	global_load_dwordx4 v[52:55], v[186:187], off offset:16
	global_load_dwordx4 v[48:51], v[188:189], off offset:16
	v_cvt_f32_i32_e32 v25, v25
	v_cvt_f32_i32_e32 v24, v24
	v_cvt_f32_i32_e32 v15, v15
	v_cvt_f32_i32_e32 v14, v14
	v_mov_b32_e32 v28, v178
	v_mov_b32_e32 v29, v178
	v_mov_b32_e32 v66, v106
	v_mov_b32_e32 v67, v106
	v_pk_mul_f32 v[28:29], v[66:67], v[28:29]
	v_mov_b32_e32 v68, v180
	v_mov_b32_e32 v69, v180
	v_pk_mul_f32 v[32:33], v[106:107], v[178:179]
	v_pk_mul_f32 v[16:17], v[28:29], v[16:17]
	v_pk_mul_f32 v[28:29], v[68:69], v[40:41]
	v_pk_mul_f32 v[40:41], v[180:181], v[174:175]
	v_pk_mul_f32 v[14:15], v[32:33], v[14:15]
	v_pk_mul_f32 v[32:33], v[28:29], v[24:25]
	v_pk_mul_f32 v[28:29], v[40:41], v[22:23]
	ds_read_b128 v[22:25], v216
	v_cvt_f32_i32_e32 v19, v19
	v_cvt_f32_i32_e32 v18, v18
	v_cvt_f32_i32_e32 v21, v21
	v_cvt_f32_i32_e32 v20, v20
	v_pk_mul_f32 v[40:41], v[68:69], v[64:65]
	v_pk_mul_f32 v[68:69], v[180:181], v[172:173]
	v_pk_mul_f32 v[64:65], v[40:41], v[20:21]
	v_pk_mul_f32 v[40:41], v[68:69], v[18:19]
	ds_read_b128 v[18:21], v215 offset:1040
	s_waitcnt lgkmcnt(1)
	v_pk_mul_f32 v[68:69], v[24:25], 0 op_sel_hi:[1,0]
	v_pk_mul_f32 v[70:71], v[22:23], 0 op_sel_hi:[1,0]
	v_cndmask_b32_e64 v100, v24, v68, s[46:47]
	v_cndmask_b32_e64 v22, v22, v70, s[46:47]
	v_cndmask_b32_e64 v23, v23, v71, s[46:47]
	v_mov_b32_dpp v68, v42 row_ror:1 row_mask:0xf bank_mask:0xf
	v_mov_b32_dpp v74, v43 row_ror:1 row_mask:0xf bank_mask:0xf
	v_cndmask_b32_e64 v101, v25, v69, s[46:47]
	v_cndmask_b32_e64 v23, v74, v23, s[38:39]
	v_cndmask_b32_e64 v22, v68, v22, s[38:39]
	v_mov_b32_dpp v24, v42 row_ror:15 row_mask:0xf bank_mask:0xf
	v_mov_b32_dpp v70, v28 row_ror:15 row_mask:0xf bank_mask:0xf
	v_mov_b32_dpp v25, v43 row_ror:15 row_mask:0xf bank_mask:0xf
	v_mov_b32_dpp v76, v29 row_ror:15 row_mask:0xf bank_mask:0xf
	v_cndmask_b32_e64 v25, v25, v76, s[40:41]
	v_cndmask_b32_e64 v24, v24, v70, s[40:41]
	v_mov_b32_dpp v86, v45 row_ror:1 row_mask:0xf bank_mask:0xf
	v_mov_b32_dpp v102, v44 row_ror:15 row_mask:0xf bank_mask:0xf
	v_mov_b32_dpp v82, v32 row_ror:15 row_mask:0xf bank_mask:0xf
	v_mov_b32_dpp v103, v45 row_ror:15 row_mask:0xf bank_mask:0xf
	v_mov_b32_dpp v88, v33 row_ror:15 row_mask:0xf bank_mask:0xf
	s_waitcnt vmcnt(3)
	v_pk_mul_f32 v[80:81], v[42:43], v[56:57]
	v_pk_mul_f32 v[98:99], v[44:45], v[58:59]
	s_waitcnt vmcnt(2)
	v_pk_fma_f32 v[22:23], v[60:61], v[22:23], v[80:81]
	s_waitcnt vmcnt(1)
	v_pk_fma_f32 v[22:23], v[52:53], v[24:25], v[22:23]
	v_cndmask_b32_e64 v25, v86, v101, s[38:39]
	v_mov_b32_dpp v80, v44 row_ror:1 row_mask:0xf bank_mask:0xf
	v_cndmask_b32_e64 v24, v80, v100, s[38:39]
	v_cndmask_b32_e64 v101, v103, v88, s[40:41]
	v_cndmask_b32_e64 v100, v102, v82, s[40:41]
	v_pk_fma_f32 v[24:25], v[62:63], v[24:25], v[98:99]
	v_pk_fma_f32 v[24:25], v[54:55], v[100:101], v[24:25]
	v_mov_b32_dpp v69, v28 row_ror:1 row_mask:0xf bank_mask:0xf
	v_mov_b32_dpp v71, v40 row_ror:1 row_mask:0xf bank_mask:0xf
	v_mov_b32_dpp v72, v40 row_ror:15 row_mask:0xf bank_mask:0xf
	v_mov_b32_dpp v94, v34 row_ror:1 row_mask:0xf bank_mask:0xf
	v_mov_b32_dpp v73, v34 row_ror:15 row_mask:0xf bank_mask:0xf
	v_mov_b32_dpp v75, v29 row_ror:1 row_mask:0xf bank_mask:0xf
	v_mov_b32_dpp v77, v41 row_ror:1 row_mask:0xf bank_mask:0xf
	v_mov_b32_dpp v78, v41 row_ror:15 row_mask:0xf bank_mask:0xf
	v_mov_b32_dpp v95, v35 row_ror:1 row_mask:0xf bank_mask:0xf
	v_mov_b32_dpp v79, v35 row_ror:15 row_mask:0xf bank_mask:0xf
	s_waitcnt vmcnt(0)
	v_pk_add_f32 v[22:23], v[48:49], v[22:23]
	v_mov_b32_dpp v81, v32 row_ror:1 row_mask:0xf bank_mask:0xf
	v_mov_b32_dpp v83, v64 row_ror:1 row_mask:0xf bank_mask:0xf
	v_mov_b32_dpp v84, v64 row_ror:15 row_mask:0xf bank_mask:0xf
	v_mov_b32_dpp v96, v36 row_ror:1 row_mask:0xf bank_mask:0xf
	v_mov_b32_dpp v85, v36 row_ror:15 row_mask:0xf bank_mask:0xf
	v_mov_b32_dpp v87, v33 row_ror:1 row_mask:0xf bank_mask:0xf
	v_mov_b32_dpp v89, v65 row_ror:1 row_mask:0xf bank_mask:0xf
	v_mov_b32_dpp v92, v65 row_ror:15 row_mask:0xf bank_mask:0xf
	v_mov_b32_dpp v97, v37 row_ror:1 row_mask:0xf bank_mask:0xf
	v_mov_b32_dpp v93, v37 row_ror:15 row_mask:0xf bank_mask:0xf
	v_pk_add_f32 v[24:25], v[50:51], v[24:25]
	s_and_saveexec_b64 s[54:55], s[50:51]
	s_cbranch_execz .LBB0_1134
	s_add_u32 s68, s3, s25
	s_addc_u32 s69, s62, s23
	v_lshl_add_u64 v[98:99], v[170:171], 2, s[68:69]
	global_store_dwordx4 v[98:99], v[42:45], off offset:16 nt
	s_nop 1
	v_add_co_u32_e32 v42, vcc, 0x5000, v98
	s_nop 1
	v_addc_co_u32_e32 v43, vcc, 0, v99, vcc
	global_store_dwordx4 v[42:43], v[22:25], off offset:2064 nt
	v_add_co_u32_e32 v42, vcc, 0xb000, v98
	s_nop 1
	v_addc_co_u32_e32 v43, vcc, 0, v99, vcc
	global_store_dwordx4 v[42:43], v[14:17], off offset:16 nt
